# also hoist the MLP-up small_gemm<2,2,3,1> prologue (2 stages, 10 LDS-DMA loads) to the start of the last unit's epilogue
# speedup vs baseline: 1.0117x; 1.0117x over previous
; template <int RA, int NP, int NS, int KT, class R8>
; DI void small_gemm(LAS unsigned char* lds, const bf16* __restrict__ A, const bf16* __restrict__ Bt, int K, int row_base, int col_base, const R8& e, int tid, int wave, int lane) {
;     ...
;     int R, Cc; pg8::stage_rc(tid * 16, R, Cc);
;     const int Rb = (R & ~31) + pg8::perm32(R & 31);
;     const bf16* asrc = A + (size_t)(row_base + R) * K + Cc;
;     const bf16* bsrc = Bt + (size_t)(col_base + Rb) * K + Cc;
;     const size_t bgrp = (size_t)64 * K;
;     const int NT = K / (64 * KT);
;     ...
;     const int r0 = row_base + 16 * (wr * RA), c0 = col_base + wc * (32 * NP);
;     float rsv[RA]; u32x4 prew[RA][NP];
; #pragma unroll
;     for (int ra = 0; ra < RA; ++ra) { rsv[ra] = 1.f; if constexpr (R8::NEED_RS) rsv[ra] = pg8::rs_of_row(e.SS, r0 + 16 * ra + fr, fq);
; #pragma unroll
;         for (int np = 0; np < NP; ++np) { prew[ra][np] = (u32x4){0u, 0u, 0u, 0u}; if constexpr (R8::HAS_PRE) prew[ra][np] = e.pre(r0 + 16 * ra + fr, c0 + 32 * np + 8 * fq); } }
;     f32x4 acc[RA][NP][2];
; #pragma unroll
;     for (int ra = 0; ra < RA; ++ra)
; #pragma unroll
;         for (int np = 0; np < NP; ++np) { acc[ra][np][0] = (f32x4){0.f, 0.f, 0.f, 0.f}; acc[ra][np][1] = (f32x4){0.f, 0.f, 0.f, 0.f}; }
;     int aoff[RA], boff[NP][2];
; #pragma unroll
;     for (int ra = 0; ra < RA; ++ra) aoff[ra] = pg8::lds_byte(16 * (wr * RA + ra) + fr, 8 * fq);
; #pragma unroll
;     for (int np = 0; np < NP; ++np)
; #pragma unroll
;         for (int n = 0; n < 2; ++n) { const int rb = wc * (32 * NP) + 32 * np + 16 * n + fr; boff[np][n] = 8192 * (1 + (rb >> 6)) + pg8::lds_byte(rb & 63, 8 * fq); }
; #pragma unroll
;     for (int s = 0; s < NS - 1; ++s) SG_STAGE(s, s);
; __global__ void __launch_bounds__(NTHREADS, 2) hybrid_fwd(Args Aval) {
;     ...
;             pg8::gemm_phase<pg8::BigEpi<pg8::RsBf16R8<1>>, pg8::GroupOrder, true, true>(lds, g, S, E, tid);
;             small_gemm<2, 2, 3, 1>(lds, (const bf16*)(ws + WS_XB), W, DM, MP + 128 * grp + 64 * (rank & 1), 256 * (rank >> 1), E.e, tid, wave, lane);
.LBB0_1383:
	s_cmp_lg_u32 s32, 0
	s_cbranch_scc0 .Lhoistb0
	s_lshl_b32 s17, s40, 6
	s_lshl_b32 s19, s27, 7
	s_and_b32 s29, s17, 64
	s_ashr_i32 s42, s41, 6
	s_or_b32 s43, s29, s19
	s_or_b32 s62, s43, 0x4000
	s_lshr_b32 s63, s42, 30
	s_add_i32 s64, s42, s63
	s_ashr_i32 s65, s64, 2
	s_lshl_b32 s66, s3, 4
	s_lshl_b32 s67, s65, 5
	s_and_b32 s76, s66, 0xffffff00
	s_add_i32 s78, s62, s67
	v_and_b32_e32 v176, 0xffffffe0, v133
	v_add_u32_e32 v178, s62, v133
	v_or_b32_e32 v180, s76, v155
	v_or_b32_e32 v182, s78, v153
	v_and_b32_e32 v177, 24, v156
	v_ashrrev_i32_e32 v179, 31, v178
	v_add_u32_e32 v176, v180, v176
	v_lshlrev_b32_e32 v184, 2, v3
	v_mov_b32_e32 v185, v2
	v_ashrrev_i32_e32 v183, 31, v182
	v_or_b32_e32 v186, 16, v182
	v_lshlrev_b64 v[178:179], 11, v[178:179]
	v_or3_b32 v176, v176, v177, v154
	v_lshl_add_u64 v[188:189], s[8:9], 0, v[184:185]
	v_lshlrev_b64 v[184:185], 7, v[182:183]
	v_ashrrev_i32_e32 v187, 31, v186
	v_mov_b32_e32 v174, v132
	v_ashrrev_i32_e32 v175, 31, v132
	v_ashrrev_i32_e32 v177, 31, v176
	v_lshl_add_u64 v[178:179], s[6:7], 0, v[178:179]
	s_lshl_b32 s79, s42, 10
	v_lshl_add_u64 v[190:191], v[188:189], 0, v[184:185]
	v_lshlrev_b64 v[192:193], 7, v[186:187]
	v_lshlrev_b64 v[176:177], 11, v[176:177]
	v_lshlrev_b64 v[180:181], 1, v[174:175]
	s_add_i32 s82, s79, 0
	s_nop 0
	v_lshl_add_u64 v[194:195], v[188:189], 0, v[192:193]
	v_lshl_add_u64 v[176:177], s[10:11], 0, v[176:177]
	v_lshl_add_u64 v[196:197], v[178:179], 0, v[180:181]
	s_mov_b32 m0, s82
	s_nop 0
	v_lshl_add_u64 v[198:199], v[176:177], 0, v[180:181]
	global_load_lds_dwordx4 v[196:197], off
	s_add_i32 m0, s82, 0x2000
	v_lshl_add_u64 v[178:179], v[198:199], 0, s[58:59]
	global_load_lds_dwordx4 v[198:199], off
	s_add_i32 m0, s82, 0x4000
	v_lshl_add_u64 v[176:177], v[198:199], 0, s[52:53]
	global_load_lds_dwordx4 v[178:179], off
	v_lshl_add_u64 v[178:179], v[198:199], 0, s[50:51]
	s_add_i32 m0, s82, 0x6000
	s_mov_b64 s[38:39], 0x20080
	global_load_lds_dwordx4 v[178:179], off
	v_lshl_add_u64 v[178:179], v[198:199], 0, s[60:61]
	s_add_i32 m0, s82, 0x8000
	s_lshl_b32 s83, s65, 15
	global_load_lds_dwordx4 v[178:179], off
	s_add_i32 m0, s82, 0xa000
	v_lshl_add_u64 v[178:179], v[196:197], 0, s[52:53]
	global_load_lds_dwordx4 v[178:179], off
	s_add_i32 m0, s82, 0xc000
	v_lshl_add_u64 v[178:179], v[198:199], 0, s[38:39]
	global_load_lds_dwordx4 v[176:177], off
	s_add_i32 m0, s82, 0xe000
	s_mov_b64 s[38:39], 0x40080
	global_load_lds_dwordx4 v[178:179], off
	v_lshl_add_u64 v[178:179], v[198:199], 0, s[38:39]
	s_add_i32 m0, s82, 0x10000
	s_mov_b64 s[38:39], 0x60080
	global_load_lds_dwordx4 v[178:179], off
	v_lshl_add_u64 v[178:179], v[198:199], 0, s[38:39]
	s_add_i32 m0, s82, 0x12000
	s_lshl_b32 s39, s65, 12
	global_load_lds_dwordx4 v[178:179], off

; DI float xsum16(float v) { const unsigned u = __float_as_uint(v); const u32x2p r = __builtin_amdgcn_permlane16_swap(u, u, false, false); return __uint_as_float(r[0]) + __uint_as_float(r[1]); }
; DI float rs_of_row(const float* SS, int row, int fq) {
;     const f32x4 a = *(const f32x4*)(SS + (size_t)row * 32 + 8 * fq), b = *(const f32x4*)(SS + (size_t)row * 32 + 8 * fq + 4);
;     float s = ((a[0] + a[1]) + (a[2] + a[3])) + ((b[0] + b[1]) + (b[2] + b[3]));
;     s = xsum32(xsum16(s));
;     return __builtin_amdgcn_rsqf(s * (1.0f / 1024.0f) + RMS_EPS);
; }
; template <int RA, int NP, int NS, int KT, class R8>
; DI void small_gemm(LAS unsigned char* lds, const bf16* __restrict__ A, const bf16* __restrict__ Bt, int K, int row_base, int col_base, const R8& e, int tid, int wave, int lane) {
;     ...
;     int R, Cc; pg8::stage_rc(tid * 16, R, Cc);
;     const int Rb = (R & ~31) + pg8::perm32(R & 31);
;     const bf16* asrc = A + (size_t)(row_base + R) * K + Cc;
;     const bf16* bsrc = Bt + (size_t)(col_base + Rb) * K + Cc;
;     const size_t bgrp = (size_t)64 * K;
;     const int NT = K / (64 * KT);
;     ...
;     const int r0 = row_base + 16 * (wr * RA), c0 = col_base + wc * (32 * NP);
;     float rsv[RA]; u32x4 prew[RA][NP];
; #pragma unroll
;     for (int ra = 0; ra < RA; ++ra) { rsv[ra] = 1.f; if constexpr (R8::NEED_RS) rsv[ra] = pg8::rs_of_row(e.SS, r0 + 16 * ra + fr, fq);
; #pragma unroll
;         for (int np = 0; np < NP; ++np) { prew[ra][np] = (u32x4){0u, 0u, 0u, 0u}; if constexpr (R8::HAS_PRE) prew[ra][np] = e.pre(r0 + 16 * ra + fr, c0 + 32 * np + 8 * fq); } }
;     f32x4 acc[RA][NP][2];
; #pragma unroll
;     for (int ra = 0; ra < RA; ++ra)
; #pragma unroll
;         for (int np = 0; np < NP; ++np) { acc[ra][np][0] = (f32x4){0.f, 0.f, 0.f, 0.f}; acc[ra][np][1] = (f32x4){0.f, 0.f, 0.f, 0.f}; }
;     int aoff[RA], boff[NP][2];
; #pragma unroll
;     for (int ra = 0; ra < RA; ++ra) aoff[ra] = pg8::lds_byte(16 * (wr * RA + ra) + fr, 8 * fq);
; #pragma unroll
;     for (int np = 0; np < NP; ++np)
; #pragma unroll
;         for (int n = 0; n < 2; ++n) { const int rb = wc * (32 * NP) + 32 * np + 16 * n + fr; boff[np][n] = 8192 * (1 + (rb >> 6)) + pg8::lds_byte(rb & 63, 8 * fq); }
; #pragma unroll
;     for (int s = 0; s < NS - 1; ++s) SG_STAGE(s, s);
.LBB0_1387:
	s_lshl_b32 s14, s40, 6
	s_lshl_b32 s13, s27, 7
	s_and_b32 s14, s14, 64
	s_ashr_i32 s12, s41, 6
	s_or_b32 s13, s14, s13
	s_or_b32 s14, s13, 0x4000
	s_lshr_b32 s13, s12, 30
	s_add_i32 s13, s12, s13
	s_ashr_i32 s13, s13, 2
	s_lshl_b32 s3, s3, 4
	s_lshl_b32 s15, s13, 5
	s_and_b32 s3, s3, 0xffffff00
	s_add_i32 s15, s14, s15
	v_and_b32_e32 v22, 0xffffffe0, v133
	v_add_u32_e32 v20, s14, v133
	v_or_b32_e32 v24, s3, v155
	v_or_b32_e32 v38, s15, v153
	v_and_b32_e32 v23, 24, v156
	v_ashrrev_i32_e32 v21, 31, v20
	v_add_u32_e32 v22, v24, v22
	v_lshlrev_b32_e32 v4, 2, v3
	v_mov_b32_e32 v5, v2
	v_ashrrev_i32_e32 v39, 31, v38
	v_or_b32_e32 v36, 16, v38
	v_lshlrev_b64 v[20:21], 11, v[20:21]
	v_or3_b32 v22, v22, v23, v154
	v_lshl_add_u64 v[12:13], s[8:9], 0, v[4:5]
	v_lshlrev_b64 v[4:5], 7, v[38:39]
	v_ashrrev_i32_e32 v37, 31, v36
	v_ashrrev_i32_e32 v133, 31, v132
	v_ashrrev_i32_e32 v23, 31, v22
	v_lshl_add_u64 v[20:21], s[6:7], 0, v[20:21]
	s_lshl_b32 s6, s12, 10
	v_lshl_add_u64 v[8:9], v[12:13], 0, v[4:5]
	v_lshlrev_b64 v[14:15], 7, v[36:37]
	v_lshlrev_b64 v[22:23], 11, v[22:23]
	v_lshlrev_b64 v[24:25], 1, v[132:133]
	s_add_i32 s6, s6, 0
	global_load_dwordx4 v[4:7], v[8:9], off
	s_nop 0
	global_load_dwordx4 v[8:11], v[8:9], off offset:16
	v_lshl_add_u64 v[16:17], v[12:13], 0, v[14:15]
	v_lshl_add_u64 v[22:23], s[10:11], 0, v[22:23]
	v_lshl_add_u64 v[42:43], v[20:21], 0, v[24:25]
	s_mov_b32 m0, s6
	global_load_dwordx4 v[12:15], v[16:17], off
	s_nop 0
	global_load_dwordx4 v[16:19], v[16:17], off offset:16
	v_lshl_add_u64 v[40:41], v[22:23], 0, v[24:25]
	s_nop 0
	s_add_i32 m0, s6, 0x2000
	v_lshl_add_u64 v[20:21], v[40:41], 0, s[58:59]
	s_nop 0
	s_add_i32 m0, s6, 0x4000
	v_lshl_add_u64 v[22:23], v[40:41], 0, s[52:53]
	s_nop 0
	v_lshl_add_u64 v[20:21], v[40:41], 0, s[50:51]
	s_add_i32 m0, s6, 0x6000
	s_mov_b64 s[8:9], 0x20080
	s_nop 0
	v_lshl_add_u64 v[20:21], v[40:41], 0, s[60:61]
	s_add_i32 m0, s6, 0x8000
	s_lshl_b32 s10, s13, 15
	s_nop 0
	s_add_i32 m0, s6, 0xa000
	v_lshl_add_u64 v[20:21], v[42:43], 0, s[52:53]
	s_nop 0
	s_add_i32 m0, s6, 0xc000
	v_lshl_add_u64 v[20:21], v[40:41], 0, s[8:9]
	s_nop 0
	s_add_i32 m0, s6, 0xe000
	s_mov_b64 s[8:9], 0x40080
	s_nop 0
	v_lshl_add_u64 v[20:21], v[40:41], 0, s[8:9]
	s_add_i32 m0, s6, 0x10000
	s_mov_b64 s[8:9], 0x60080
	s_nop 0
	v_lshl_add_u64 v[20:21], v[40:41], 0, s[8:9]
	s_add_i32 m0, s6, 0x12000
	s_lshl_b32 s9, s13, 12
	s_nop 0
	s_lshl_b32 s8, s12, 13
	v_mov_b32_e32 v28, 0
	s_mov_b32 s7, 2
	s_add_i32 s8, s8, 0
	s_mov_b32 s11, 0
	v_mov_b32_e32 v29, v28
	v_mov_b32_e32 v30, v28
	v_mov_b32_e32 v31, v28
	v_mov_b32_e32 v32, v28
	v_mov_b32_e32 v33, v28
	v_mov_b32_e32 v34, v28
	v_mov_b32_e32 v35, v28
	v_mov_b32_e32 v20, v28
	v_mov_b32_e32 v21, v28
	v_mov_b32_e32 v22, v28
	v_mov_b32_e32 v23, v28
	v_mov_b32_e32 v24, v28
	v_mov_b32_e32 v25, v28
	v_mov_b32_e32 v26, v28
	v_mov_b32_e32 v27, v28
	s_waitcnt vmcnt(0)
	v_add_f32_e32 v4, v4, v5
	v_add_f32_e32 v5, v6, v7
	v_add_f32_e32 v6, v8, v9
	v_add_f32_e32 v7, v10, v11
	v_add_f32_e32 v4, v4, v5
	v_add_f32_e32 v5, v6, v7
	v_add_f32_e32 v44, v4, v5
	v_add_f32_e32 v4, v12, v13
	v_add_f32_e32 v5, v14, v15
	v_add_f32_e32 v4, v4, v5
	v_add_f32_e32 v5, v16, v17
	v_add_f32_e32 v6, v18, v19
	v_add_f32_e32 v5, v5, v6
	v_add_f32_e32 v46, v4, v5
	v_and_b32_e32 v4, 48, v152
	v_lshlrev_b32_e32 v6, 2, v153
	v_lshlrev_b32_e32 v7, 6, v152
	v_lshlrev_b32_e32 v8, 2, v152
	v_lshl_or_b32 v5, v153, 6, v4
	v_and_b32_e32 v6, 32, v6
	v_and_b32_e32 v7, 0x3c0, v7
	v_and_b32_e32 v8, 32, v8
	v_mov_b32_e32 v45, v44
	v_mov_b32_e32 v47, v46
	v_bitop3_b32 v4, v7, v8, v4 bitop3:0x36
	v_bitop3_b32 v49, v5, s9, v6 bitop3:0xde
	v_permlane16_swap_b32_e32 v44, v45
	v_permlane16_swap_b32_e32 v46, v47
	v_subrev_u32_e32 v48, s10, v4
	v_or_b32_e32 v50, 0xc00, v49
	v_or_b32_e32 v51, 0x800, v49
	s_mov_b32 s9, 0
	s_movk_i32 s10, 0x80
	v_mov_b32_e32 v12, v28
	v_mov_b32_e32 v13, v28
	v_mov_b32_e32 v14, v28
	v_mov_b32_e32 v15, v28
	v_mov_b32_e32 v16, v28
	v_mov_b32_e32 v17, v28
	v_mov_b32_e32 v18, v28
	v_mov_b32_e32 v19, v28
	v_mov_b32_e32 v4, v28
	v_mov_b32_e32 v5, v28
	v_mov_b32_e32 v6, v28
	v_mov_b32_e32 v7, v28
	v_mov_b32_e32 v8, v28
	v_mov_b32_e32 v9, v28
	v_mov_b32_e32 v10, v28
	v_mov_b32_e32 v11, v28
